# position FFT: the item's 16 row loads per thread issued back to back instead of one dependent round trip per loop trip
# speedup vs baseline: 1.0087x; 1.0011x over previous
; __device__ __forceinline__ void phase_fft(const Params& p, LAS unsigned char* lds) {
;     ...
;     for (int it = blockIdx.x; it < 256; it += gridDim.x) {
;         const int b = it >> 7, c0 = 4 * (it & 127);
;         __syncthreads();
;         for (int t = tid; t < SEQ; t += 512) { const h16x4 v = *(const h16x4*)(FD + ((size_t)(it & 127) * NTOK + b * SEQ + t) * 4);
;             X0[t] = (f32x2){(float)v[0], (float)v[1]}; X1[t] = (f32x2){(float)v[2], (float)v[3]}; }
;         __syncthreads();
.LBB0_579:
	global_load_dwordx2 v[56:57], v[2:3], off
	v_lshl_add_u64 v[2:3], v[2:3], 0, s[8:9]
	global_load_dwordx2 v[58:59], v[2:3], off
	v_lshl_add_u64 v[2:3], v[2:3], 0, s[8:9]
	global_load_dwordx2 v[60:61], v[2:3], off
	v_lshl_add_u64 v[2:3], v[2:3], 0, s[8:9]
	global_load_dwordx2 v[62:63], v[2:3], off
	v_lshl_add_u64 v[2:3], v[2:3], 0, s[8:9]
	global_load_dwordx2 v[64:65], v[2:3], off
	v_lshl_add_u64 v[2:3], v[2:3], 0, s[8:9]
	global_load_dwordx2 v[66:67], v[2:3], off
	v_lshl_add_u64 v[2:3], v[2:3], 0, s[8:9]
	global_load_dwordx2 v[68:69], v[2:3], off
	v_lshl_add_u64 v[2:3], v[2:3], 0, s[8:9]
	global_load_dwordx2 v[70:71], v[2:3], off
	v_lshl_add_u64 v[2:3], v[2:3], 0, s[8:9]
	global_load_dwordx2 v[72:73], v[2:3], off
	v_lshl_add_u64 v[2:3], v[2:3], 0, s[8:9]
	global_load_dwordx2 v[74:75], v[2:3], off
	v_lshl_add_u64 v[2:3], v[2:3], 0, s[8:9]
	global_load_dwordx2 v[76:77], v[2:3], off
	v_lshl_add_u64 v[2:3], v[2:3], 0, s[8:9]
	global_load_dwordx2 v[78:79], v[2:3], off
	v_lshl_add_u64 v[2:3], v[2:3], 0, s[8:9]
	global_load_dwordx2 v[80:81], v[2:3], off
	v_lshl_add_u64 v[2:3], v[2:3], 0, s[8:9]
	global_load_dwordx2 v[82:83], v[2:3], off
	v_lshl_add_u64 v[2:3], v[2:3], 0, s[8:9]
	global_load_dwordx2 v[84:85], v[2:3], off
	v_lshl_add_u64 v[2:3], v[2:3], 0, s[8:9]
	global_load_dwordx2 v[86:87], v[2:3], off
	v_lshl_add_u64 v[2:3], v[2:3], 0, s[8:9]
	s_waitcnt vmcnt(14)
	v_cvt_f32_f16_sdwa v15, v56 dst_sel:DWORD dst_unused:UNUSED_PAD src0_sel:WORD_1
	v_cvt_f32_f16_e32 v14, v56
	v_cvt_f32_f16_sdwa v17, v57 dst_sel:DWORD dst_unused:UNUSED_PAD src0_sel:WORD_1
	v_cvt_f32_f16_e32 v16, v57
	v_add_u32_e32 v11, 0x10000, v9
	ds_write_b64 v9, v[14:15]
	ds_write_b64 v11, v[16:17]
	v_add_u32_e32 v9, 0x1000, v9
	v_cvt_f32_f16_sdwa v15, v58 dst_sel:DWORD dst_unused:UNUSED_PAD src0_sel:WORD_1
	v_cvt_f32_f16_e32 v14, v58
	v_cvt_f32_f16_sdwa v17, v59 dst_sel:DWORD dst_unused:UNUSED_PAD src0_sel:WORD_1
	v_cvt_f32_f16_e32 v16, v59
	v_add_u32_e32 v11, 0x10000, v9
	ds_write_b64 v9, v[14:15]
	ds_write_b64 v11, v[16:17]
	v_add_u32_e32 v9, 0x1000, v9
	s_waitcnt vmcnt(12)
	v_cvt_f32_f16_sdwa v15, v60 dst_sel:DWORD dst_unused:UNUSED_PAD src0_sel:WORD_1
	v_cvt_f32_f16_e32 v14, v60
	v_cvt_f32_f16_sdwa v17, v61 dst_sel:DWORD dst_unused:UNUSED_PAD src0_sel:WORD_1
	v_cvt_f32_f16_e32 v16, v61
	v_add_u32_e32 v11, 0x10000, v9
	ds_write_b64 v9, v[14:15]
	ds_write_b64 v11, v[16:17]
	v_add_u32_e32 v9, 0x1000, v9
	v_cvt_f32_f16_sdwa v15, v62 dst_sel:DWORD dst_unused:UNUSED_PAD src0_sel:WORD_1
	v_cvt_f32_f16_e32 v14, v62
	v_cvt_f32_f16_sdwa v17, v63 dst_sel:DWORD dst_unused:UNUSED_PAD src0_sel:WORD_1
	v_cvt_f32_f16_e32 v16, v63
	v_add_u32_e32 v11, 0x10000, v9
	ds_write_b64 v9, v[14:15]
	ds_write_b64 v11, v[16:17]
	v_add_u32_e32 v9, 0x1000, v9
	s_waitcnt vmcnt(10)
	v_cvt_f32_f16_sdwa v15, v64 dst_sel:DWORD dst_unused:UNUSED_PAD src0_sel:WORD_1
	v_cvt_f32_f16_e32 v14, v64
	v_cvt_f32_f16_sdwa v17, v65 dst_sel:DWORD dst_unused:UNUSED_PAD src0_sel:WORD_1
	v_cvt_f32_f16_e32 v16, v65
	v_add_u32_e32 v11, 0x10000, v9
	ds_write_b64 v9, v[14:15]
	ds_write_b64 v11, v[16:17]
	v_add_u32_e32 v9, 0x1000, v9
	v_cvt_f32_f16_sdwa v15, v66 dst_sel:DWORD dst_unused:UNUSED_PAD src0_sel:WORD_1
	v_cvt_f32_f16_e32 v14, v66
	v_cvt_f32_f16_sdwa v17, v67 dst_sel:DWORD dst_unused:UNUSED_PAD src0_sel:WORD_1
	v_cvt_f32_f16_e32 v16, v67
	v_add_u32_e32 v11, 0x10000, v9
	ds_write_b64 v9, v[14:15]
	ds_write_b64 v11, v[16:17]
	v_add_u32_e32 v9, 0x1000, v9
	s_waitcnt vmcnt(8)
	v_cvt_f32_f16_sdwa v15, v68 dst_sel:DWORD dst_unused:UNUSED_PAD src0_sel:WORD_1
	v_cvt_f32_f16_e32 v14, v68
	v_cvt_f32_f16_sdwa v17, v69 dst_sel:DWORD dst_unused:UNUSED_PAD src0_sel:WORD_1
	v_cvt_f32_f16_e32 v16, v69
	v_add_u32_e32 v11, 0x10000, v9
	ds_write_b64 v9, v[14:15]
	ds_write_b64 v11, v[16:17]
	v_add_u32_e32 v9, 0x1000, v9
	v_cvt_f32_f16_sdwa v15, v70 dst_sel:DWORD dst_unused:UNUSED_PAD src0_sel:WORD_1
	v_cvt_f32_f16_e32 v14, v70
	v_cvt_f32_f16_sdwa v17, v71 dst_sel:DWORD dst_unused:UNUSED_PAD src0_sel:WORD_1
	v_cvt_f32_f16_e32 v16, v71
	v_add_u32_e32 v11, 0x10000, v9
	ds_write_b64 v9, v[14:15]
	ds_write_b64 v11, v[16:17]
	v_add_u32_e32 v9, 0x1000, v9
	s_waitcnt vmcnt(6)
	v_cvt_f32_f16_sdwa v15, v72 dst_sel:DWORD dst_unused:UNUSED_PAD src0_sel:WORD_1
	v_cvt_f32_f16_e32 v14, v72
	v_cvt_f32_f16_sdwa v17, v73 dst_sel:DWORD dst_unused:UNUSED_PAD src0_sel:WORD_1
	v_cvt_f32_f16_e32 v16, v73
	v_add_u32_e32 v11, 0x10000, v9
	ds_write_b64 v9, v[14:15]
	ds_write_b64 v11, v[16:17]
	v_add_u32_e32 v9, 0x1000, v9
	v_cvt_f32_f16_sdwa v15, v74 dst_sel:DWORD dst_unused:UNUSED_PAD src0_sel:WORD_1
	v_cvt_f32_f16_e32 v14, v74
	v_cvt_f32_f16_sdwa v17, v75 dst_sel:DWORD dst_unused:UNUSED_PAD src0_sel:WORD_1
	v_cvt_f32_f16_e32 v16, v75
	v_add_u32_e32 v11, 0x10000, v9
	ds_write_b64 v9, v[14:15]
	ds_write_b64 v11, v[16:17]
	v_add_u32_e32 v9, 0x1000, v9
	s_waitcnt vmcnt(4)
	v_cvt_f32_f16_sdwa v15, v76 dst_sel:DWORD dst_unused:UNUSED_PAD src0_sel:WORD_1
	v_cvt_f32_f16_e32 v14, v76
	v_cvt_f32_f16_sdwa v17, v77 dst_sel:DWORD dst_unused:UNUSED_PAD src0_sel:WORD_1
	v_cvt_f32_f16_e32 v16, v77
	v_add_u32_e32 v11, 0x10000, v9
	ds_write_b64 v9, v[14:15]
	ds_write_b64 v11, v[16:17]
	v_add_u32_e32 v9, 0x1000, v9
	v_cvt_f32_f16_sdwa v15, v78 dst_sel:DWORD dst_unused:UNUSED_PAD src0_sel:WORD_1
	v_cvt_f32_f16_e32 v14, v78
	v_cvt_f32_f16_sdwa v17, v79 dst_sel:DWORD dst_unused:UNUSED_PAD src0_sel:WORD_1
	v_cvt_f32_f16_e32 v16, v79
	v_add_u32_e32 v11, 0x10000, v9
	ds_write_b64 v9, v[14:15]
	ds_write_b64 v11, v[16:17]
	v_add_u32_e32 v9, 0x1000, v9
	s_waitcnt vmcnt(2)
	v_cvt_f32_f16_sdwa v15, v80 dst_sel:DWORD dst_unused:UNUSED_PAD src0_sel:WORD_1
	v_cvt_f32_f16_e32 v14, v80
	v_cvt_f32_f16_sdwa v17, v81 dst_sel:DWORD dst_unused:UNUSED_PAD src0_sel:WORD_1
	v_cvt_f32_f16_e32 v16, v81
	v_add_u32_e32 v11, 0x10000, v9
	ds_write_b64 v9, v[14:15]
	ds_write_b64 v11, v[16:17]
	v_add_u32_e32 v9, 0x1000, v9
	v_cvt_f32_f16_sdwa v15, v82 dst_sel:DWORD dst_unused:UNUSED_PAD src0_sel:WORD_1
	v_cvt_f32_f16_e32 v14, v82
	v_cvt_f32_f16_sdwa v17, v83 dst_sel:DWORD dst_unused:UNUSED_PAD src0_sel:WORD_1
	v_cvt_f32_f16_e32 v16, v83
	v_add_u32_e32 v11, 0x10000, v9
	ds_write_b64 v9, v[14:15]
	ds_write_b64 v11, v[16:17]
	v_add_u32_e32 v9, 0x1000, v9
	s_waitcnt vmcnt(0)
	v_cvt_f32_f16_sdwa v15, v84 dst_sel:DWORD dst_unused:UNUSED_PAD src0_sel:WORD_1
	v_cvt_f32_f16_e32 v14, v84
	v_cvt_f32_f16_sdwa v17, v85 dst_sel:DWORD dst_unused:UNUSED_PAD src0_sel:WORD_1
	v_cvt_f32_f16_e32 v16, v85
	v_add_u32_e32 v11, 0x10000, v9
	ds_write_b64 v9, v[14:15]
	ds_write_b64 v11, v[16:17]
	v_add_u32_e32 v9, 0x1000, v9
	v_cvt_f32_f16_sdwa v15, v86 dst_sel:DWORD dst_unused:UNUSED_PAD src0_sel:WORD_1
	v_cvt_f32_f16_e32 v14, v86
	v_cvt_f32_f16_sdwa v17, v87 dst_sel:DWORD dst_unused:UNUSED_PAD src0_sel:WORD_1
	v_cvt_f32_f16_e32 v16, v87
	v_add_u32_e32 v11, 0x10000, v9
	ds_write_b64 v9, v[14:15]
	ds_write_b64 v11, v[16:17]
	v_add_u32_e32 v9, 0x1000, v9
	s_or_b64 exec, exec, s[0:1]
	s_mov_b32 s12, 0
	s_waitcnt lgkmcnt(0)
	s_barrier
